# v41 + MLA steady step: row sums with v_pk_add_f32 (17 adds instead of 34), exps in place, hand-scheduled exp/cvt/PV section
# speedup vs baseline: 1.0054x; 1.0054x over previous
.LBB0_1482:
	v_exp_f32_e32 v66, v66
	v_exp_f32_e32 v67, v67
	v_exp_f32_e32 v68, v68
	v_exp_f32_e32 v69, v69
	v_exp_f32_e32 v70, v70
	v_exp_f32_e32 v71, v71
	v_exp_f32_e32 v72, v72
	v_exp_f32_e32 v73, v73
	v_pk_add_f32 v[154:155], v[66:67], v[68:69]
	v_pk_add_f32 v[156:157], v[70:71], v[72:73]
	v_pk_add_f32 v[158:159], v[154:155], v[156:157]
	v_cvt_pk_bf16_f32 v66, v66, v67
	v_cvt_pk_bf16_f32 v67, v68, v69
	v_cvt_pk_bf16_f32 v68, v70, v71
	v_cvt_pk_bf16_f32 v69, v72, v73
	v_exp_f32_e32 v74, v74
	v_exp_f32_e32 v75, v75
	v_mfma_f32_32x32x16_bf16 v[18:33], v[66:69], v[150:153], v[18:33]
	v_exp_f32_e32 v76, v76
	v_exp_f32_e32 v77, v77
	v_exp_f32_e32 v78, v78
	s_waitcnt lgkmcnt(6)
	v_mfma_f32_32x32x16_bf16 v[34:49], v[66:69], v[134:137], v[34:49]
	v_exp_f32_e32 v79, v79
	v_exp_f32_e32 v80, v80
	v_exp_f32_e32 v81, v81
	v_pk_add_f32 v[154:155], v[74:75], v[76:77]
	v_pk_add_f32 v[156:157], v[78:79], v[80:81]
	v_pk_add_f32 v[160:161], v[154:155], v[156:157]
	v_cvt_pk_bf16_f32 v70, v74, v75
	v_cvt_pk_bf16_f32 v71, v76, v77
	v_cvt_pk_bf16_f32 v72, v78, v79
	v_cvt_pk_bf16_f32 v73, v80, v81
	v_exp_f32_e32 v82, v82
	v_exp_f32_e32 v83, v83
	v_mfma_f32_32x32x16_bf16 v[18:33], v[70:73], v[146:149], v[18:33]
	v_exp_f32_e32 v84, v84
	v_exp_f32_e32 v85, v85
	v_exp_f32_e32 v86, v86
	s_waitcnt lgkmcnt(4)
	v_mfma_f32_32x32x16_bf16 v[34:49], v[70:73], v[130:133], v[34:49]
	v_exp_f32_e32 v87, v87
	v_exp_f32_e32 v88, v88
	v_exp_f32_e32 v89, v89
	v_pk_add_f32 v[154:155], v[82:83], v[84:85]
	v_pk_add_f32 v[156:157], v[86:87], v[88:89]
	v_pk_add_f32 v[162:163], v[154:155], v[156:157]
	v_cvt_pk_bf16_f32 v74, v82, v83
	v_cvt_pk_bf16_f32 v75, v84, v85
	v_cvt_pk_bf16_f32 v76, v86, v87
	v_cvt_pk_bf16_f32 v77, v88, v89
	v_exp_f32_e32 v90, v90
	v_exp_f32_e32 v91, v91
	v_mfma_f32_32x32x16_bf16 v[18:33], v[74:77], v[142:145], v[18:33]
	v_exp_f32_e32 v92, v92
	v_exp_f32_e32 v93, v93
	v_exp_f32_e32 v94, v94
	s_waitcnt lgkmcnt(2)
	v_mfma_f32_32x32x16_bf16 v[34:49], v[74:77], v[126:129], v[34:49]
	v_exp_f32_e32 v95, v95
	v_exp_f32_e32 v96, v96
	v_exp_f32_e32 v97, v97
	v_pk_add_f32 v[154:155], v[90:91], v[92:93]
	v_pk_add_f32 v[156:157], v[94:95], v[96:97]
	v_pk_add_f32 v[164:165], v[154:155], v[156:157]
	v_cvt_pk_bf16_f32 v78, v90, v91
	v_cvt_pk_bf16_f32 v79, v92, v93
	v_cvt_pk_bf16_f32 v80, v94, v95
	v_cvt_pk_bf16_f32 v81, v96, v97
	v_pk_add_f32 v[158:159], v[158:159], v[160:161]
	s_add_u32 s24, s24, 0x10000
	s_addc_u32 s25, s25, 0
	v_mfma_f32_32x32x16_bf16 v[18:33], v[78:81], v[138:141], v[18:33]
	v_pk_add_f32 v[162:163], v[162:163], v[164:165]
	s_add_u32 s22, s22, 0x1000
	s_addc_u32 s23, s23, 0
	s_waitcnt lgkmcnt(0)
	v_mfma_f32_32x32x16_bf16 v[34:49], v[78:81], v[122:125], v[34:49]
	v_pk_add_f32 v[158:159], v[158:159], v[162:163]
	s_waitcnt vmcnt(0) lgkmcnt(0)
	s_barrier
	v_add_f32_e32 v158, v158, v159
	s_cmp_eq_u32 s24, 0x200000
	v_add_f32_e32 v173, v173, v158
	s_cbranch_scc1 .LBB0_1484
	s_mov_b32 s49, s57
	s_branch .LBB0_1476
